# v53 + layer-0 ffn_down and PLE gate/proj weight conversion moved out of phase 0 into phase 3, staggered around the gates GEMM tiles
# speedup vs baseline: 1.0389x; 1.0074x over previous
; #define LAS __attribute__((address_space(3)))
; __device__ __forceinline__ void xpose_item(const float* src, int ld, bf16_t* dst, int K, int k0, LAS float* scr, int lane, const float* gk) {
;     if (src) {
; #pragma unroll 8
;         for (int i = 0; i < 32; ++i) { const int kk = 2 * i + (lane >> 5); scr[kk * 33 + (lane & 31)] = __builtin_nontemporal_load(src + (size_t)(k0 + kk) * ld + (lane & 31)); }
;     } else {
; #pragma unroll 8
;         for (int i = 0; i < 32; ++i) { const int kk = 2 * i + (lane >> 5); scr[kk * 33 + (lane & 31)] = 0.f; }
;     }
;     const int c = lane & 7;
;     f32x4 g0 = (f32x4){1.f, 1.f, 1.f, 1.f}, g1 = g0;
;     if (gk) { g0 = *(const f32x4*)(gk + k0 + 8 * c); g1 = *(const f32x4*)(gk + k0 + 8 * c + 4); }
; __global__ void __launch_bounds__(512) mega(Args a_byval) {
;     ...
;         case 3: if (!PH_ON(3)) break; {
;             pg8::Gemm g{(const bf16_t*)(ws + WS_XRC), (const bf16_t*)(ws + WS_W_GATE), T, 4096, 256, 2048, 256, 2}; pg8::StaticOrder S; S.init(T, 4096, G, bid);
;             EpiGates E{(const bf16_t*)(ws + WS_XRC), a.in[10], a.in[12], (const float*)(ws + WS_SPT), (bf16_t*)(ws + WS_AA), (bf16_t*)(ws + WS_BB)}; pg8::gemm_phase(lds, g, S, E, tid);
.LBB0_478:
	v_readlane_b32 s0, v254, 61
	v_readlane_b32 s1, v254, 62
	s_andn2_b64 vcc, exec, s[0:1]
	s_cbranch_vccnz .LBB0_586
	s_cmp_gt_i32 s76, 1
	s_mov_b64 s[0:1], -1
	s_cbranch_scc0 .LBB0_521
	s_cmp_gt_i32 s76, 2
	s_cbranch_scc0 .LBB0_509
	s_cmp_lg_u32 s76, 3
	s_cbranch_scc1 .Lsgp3e_done
	v_readlane_b32 s59, v255, 5
	s_cmpk_lg_i32 s59, 0x100
	s_cbranch_scc1 .Lsgp3e_done
	s_cmpk_gt_i32 s94, 0x7f
	s_cbranch_scc1 .Lsgp3e_done
	s_lshl_b32 s59, s94, 3
	s_add_i32 s59, s59, s95
	s_mul_i32 s64, s95, 0x2100
	v_and_b32_e32 v2, 31, v200
	v_lshrrev_b32_e32 v3, 5, v200
	v_lshlrev_b32_e32 v4, 2, v2
	v_mul_u32_u24_e32 v6, 0x84, v3
	v_add3_u32 v6, v6, v4, s64
	v_and_b32_e32 v7, 7, v200
	v_lshrrev_b32_e32 v8, 3, v200
	v_mul_u32_u24_e32 v9, 0x420, v7
	v_lshl_add_u32 v9, v8, 2, v9
	v_add_u32_e32 v9, s64, v9
	s_cmpk_ge_i32 s59, 0x1600
	s_cbranch_scc1 .Lxpf0p3e_end
	s_load_dwordx2 s[60:61], s[92:93], 0xc8
	s_load_dwordx2 s[62:63], s[92:93], 0xe8
	v_mov_b32_e32 v5, 0x2000
	v_mul_u32_u24_e32 v5, v3, v5
	v_add_u32_e32 v5, v5, v4
	v_mov_b32_e32 v10, 0x2c00
	v_mul_u32_u24_e32 v10, v8, v10
	v_lshl_add_u32 v12, v7, 4, v10
	v_add_u32_e32 v13, 0x16000, v12
	v_add_u32_e32 v14, 0x2c000, v12
	v_add_u32_e32 v15, 0x42000, v12
	s_waitcnt lgkmcnt(0)
	s_add_u32 s62, s62, 0x1f800000
	s_addc_u32 s63, s63, 0
	s_lshr_b32 s64, s59, 6
	s_and_b32 s65, s59, 63
	s_mul_i32 s66, s64, 0x80000
	s_lshl_b32 s67, s65, 7
	s_add_i32 s66, s66, s67
	s_add_u32 s66, s60, s66
	s_addc_u32 s67, s61, 0
	v_mov_b32_e32 v11, v5
	global_load_dword v20, v11, s[66:67] nt
	v_add_u32_e32 v11, 0x4000, v11
	global_load_dword v21, v11, s[66:67] nt
	v_add_u32_e32 v11, 0x4000, v11
	global_load_dword v22, v11, s[66:67] nt
	v_add_u32_e32 v11, 0x4000, v11
	global_load_dword v23, v11, s[66:67] nt
	v_add_u32_e32 v11, 0x4000, v11
	global_load_dword v24, v11, s[66:67] nt
	v_add_u32_e32 v11, 0x4000, v11
	global_load_dword v25, v11, s[66:67] nt
	v_add_u32_e32 v11, 0x4000, v11
	global_load_dword v26, v11, s[66:67] nt
	v_add_u32_e32 v11, 0x4000, v11
	global_load_dword v27, v11, s[66:67] nt
	v_add_u32_e32 v11, 0x4000, v11
	global_load_dword v28, v11, s[66:67] nt
	v_add_u32_e32 v11, 0x4000, v11
	global_load_dword v29, v11, s[66:67] nt
	v_add_u32_e32 v11, 0x4000, v11
	global_load_dword v30, v11, s[66:67] nt
	v_add_u32_e32 v11, 0x4000, v11
	global_load_dword v31, v11, s[66:67] nt
	v_add_u32_e32 v11, 0x4000, v11
	global_load_dword v32, v11, s[66:67] nt
	v_add_u32_e32 v11, 0x4000, v11
	global_load_dword v33, v11, s[66:67] nt
	v_add_u32_e32 v11, 0x4000, v11
	global_load_dword v34, v11, s[66:67] nt
	v_add_u32_e32 v11, 0x4000, v11
	global_load_dword v35, v11, s[66:67] nt
	v_add_u32_e32 v11, 0x4000, v11
	global_load_dword v36, v11, s[66:67] nt
	v_add_u32_e32 v11, 0x4000, v11
	global_load_dword v37, v11, s[66:67] nt
	v_add_u32_e32 v11, 0x4000, v11
	global_load_dword v38, v11, s[66:67] nt
	v_add_u32_e32 v11, 0x4000, v11
	global_load_dword v39, v11, s[66:67] nt
	v_add_u32_e32 v11, 0x4000, v11
	global_load_dword v40, v11, s[66:67] nt
	v_add_u32_e32 v11, 0x4000, v11
	global_load_dword v41, v11, s[66:67] nt
	v_add_u32_e32 v11, 0x4000, v11
	global_load_dword v42, v11, s[66:67] nt
	v_add_u32_e32 v11, 0x4000, v11
	global_load_dword v43, v11, s[66:67] nt
	v_add_u32_e32 v11, 0x4000, v11
	global_load_dword v44, v11, s[66:67] nt
	v_add_u32_e32 v11, 0x4000, v11
	global_load_dword v45, v11, s[66:67] nt
	v_add_u32_e32 v11, 0x4000, v11
	global_load_dword v46, v11, s[66:67] nt
	v_add_u32_e32 v11, 0x4000, v11
	global_load_dword v47, v11, s[66:67] nt
	v_add_u32_e32 v11, 0x4000, v11
	global_load_dword v48, v11, s[66:67] nt
	v_add_u32_e32 v11, 0x4000, v11
	global_load_dword v49, v11, s[66:67] nt
	v_add_u32_e32 v11, 0x4000, v11
	global_load_dword v50, v11, s[66:67] nt
	v_add_u32_e32 v11, 0x4000, v11
	global_load_dword v51, v11, s[66:67] nt
.Lxpf0p3e_loop:
	s_add_i32 s32, s59, 0x800
	s_cmpk_lt_i32 s32, 0x1600
	s_cbranch_scc0 .Lxpf0p3e_dumB
	s_lshr_b32 s64, s32, 6
	s_and_b32 s65, s32, 63
	s_mul_i32 s66, s64, 0x80000
	s_lshl_b32 s67, s65, 7
	s_add_i32 s66, s66, s67
	s_add_u32 s66, s60, s66
	s_addc_u32 s67, s61, 0
	v_mov_b32_e32 v11, v5
	global_load_dword v108, v11, s[66:67] nt
	v_add_u32_e32 v11, 0x4000, v11
	global_load_dword v109, v11, s[66:67] nt
	v_add_u32_e32 v11, 0x4000, v11
	global_load_dword v110, v11, s[66:67] nt
	v_add_u32_e32 v11, 0x4000, v11
	global_load_dword v111, v11, s[66:67] nt
	v_add_u32_e32 v11, 0x4000, v11
	global_load_dword v112, v11, s[66:67] nt
	v_add_u32_e32 v11, 0x4000, v11
	global_load_dword v113, v11, s[66:67] nt
	v_add_u32_e32 v11, 0x4000, v11
	global_load_dword v114, v11, s[66:67] nt
	v_add_u32_e32 v11, 0x4000, v11
	global_load_dword v115, v11, s[66:67] nt
	v_add_u32_e32 v11, 0x4000, v11
	global_load_dword v116, v11, s[66:67] nt
	v_add_u32_e32 v11, 0x4000, v11
	global_load_dword v117, v11, s[66:67] nt
	v_add_u32_e32 v11, 0x4000, v11
	global_load_dword v118, v11, s[66:67] nt
	v_add_u32_e32 v11, 0x4000, v11
	global_load_dword v119, v11, s[66:67] nt
	v_add_u32_e32 v11, 0x4000, v11
	global_load_dword v120, v11, s[66:67] nt
	v_add_u32_e32 v11, 0x4000, v11
	global_load_dword v121, v11, s[66:67] nt
	v_add_u32_e32 v11, 0x4000, v11
	global_load_dword v122, v11, s[66:67] nt
	v_add_u32_e32 v11, 0x4000, v11
	global_load_dword v123, v11, s[66:67] nt
	v_add_u32_e32 v11, 0x4000, v11
	global_load_dword v124, v11, s[66:67] nt
	v_add_u32_e32 v11, 0x4000, v11
	global_load_dword v125, v11, s[66:67] nt
	v_add_u32_e32 v11, 0x4000, v11
	global_load_dword v126, v11, s[66:67] nt
	v_add_u32_e32 v11, 0x4000, v11
	global_load_dword v127, v11, s[66:67] nt
	v_add_u32_e32 v11, 0x4000, v11
	global_load_dword v128, v11, s[66:67] nt
	v_add_u32_e32 v11, 0x4000, v11
	global_load_dword v129, v11, s[66:67] nt
	v_add_u32_e32 v11, 0x4000, v11
	global_load_dword v130, v11, s[66:67] nt
	v_add_u32_e32 v11, 0x4000, v11
	global_load_dword v131, v11, s[66:67] nt
	v_add_u32_e32 v11, 0x4000, v11
	global_load_dword v132, v11, s[66:67] nt
	v_add_u32_e32 v11, 0x4000, v11
	global_load_dword v133, v11, s[66:67] nt
	v_add_u32_e32 v11, 0x4000, v11
	global_load_dword v134, v11, s[66:67] nt
	v_add_u32_e32 v11, 0x4000, v11
	global_load_dword v135, v11, s[66:67] nt
	v_add_u32_e32 v11, 0x4000, v11
	global_load_dword v136, v11, s[66:67] nt
	v_add_u32_e32 v11, 0x4000, v11
	global_load_dword v137, v11, s[66:67] nt
	v_add_u32_e32 v11, 0x4000, v11
	global_load_dword v138, v11, s[66:67] nt
	v_add_u32_e32 v11, 0x4000, v11
	global_load_dword v139, v11, s[66:67] nt
	s_branch .Lxpf0p3e_procA

; #define LAS __attribute__((address_space(3)))
; __device__ __forceinline__ unsigned cvt_pk_bf16(float lo, float hi) { unsigned r; asm volatile("v_cvt_pk_bf16_f32 %0, %1, %2" : "=v"(r) : "v"(lo), "v"(hi)); return r; }
; __device__ __forceinline__ void xpose_item(const float* src, int ld, bf16_t* dst, int K, int k0, LAS float* scr, int lane, const float* gk) {
;     ...
;         for (int i = 0; i < 32; ++i) { const int kk = 2 * i + (lane >> 5); scr[kk * 33 + (lane & 31)] = __builtin_nontemporal_load(src + (size_t)(k0 + kk) * ld + (lane & 31)); }
;     } else {
; #pragma unroll 8
;         for (int i = 0; i < 32; ++i) { const int kk = 2 * i + (lane >> 5); scr[kk * 33 + (lane & 31)] = 0.f; }
;     }
;     const int c = lane & 7;
;     f32x4 g0 = (f32x4){1.f, 1.f, 1.f, 1.f}, g1 = g0;
;     if (gk) { g0 = *(const f32x4*)(gk + k0 + 8 * c); g1 = *(const f32x4*)(gk + k0 + 8 * c + 4); }
;     asm volatile("s_waitcnt lgkmcnt(0)" ::: "memory");
; #pragma unroll
;     for (int j = 0; j < 4; ++j) { const int n = (lane >> 3) + 8 * j; const LAS float* s = scr + (8 * c) * 33 + n;
;         u32x4 o; o.x = cvt_pk_bf16(s[0 * 33] * g0[0], s[1 * 33] * g0[1]); o.y = cvt_pk_bf16(s[2 * 33] * g0[2], s[3 * 33] * g0[3]); o.z = cvt_pk_bf16(s[4 * 33] * g1[0], s[5 * 33] * g1[1]); o.w = cvt_pk_bf16(s[6 * 33] * g1[2], s[7 * 33] * g1[3]);
;         *(u32x4*)(dst + (size_t)n * K + k0 + 8 * c) = o; }
.Lxpf0p3e_procA:
	s_lshr_b32 s64, s59, 6
	s_and_b32 s65, s59, 63
	s_mul_i32 s68, s65, 0x58000
	s_lshl_b32 s64, s64, 7
	s_add_i32 s68, s68, s64
	s_add_u32 s64, s62, s68
	s_addc_u32 s65, s63, 0
	s_waitcnt vmcnt(63)
	ds_write_b32 v6, v20 offset:0
	s_waitcnt vmcnt(62)
	ds_write_b32 v6, v21 offset:264
	s_waitcnt vmcnt(61)
	ds_write_b32 v6, v22 offset:528
	s_waitcnt vmcnt(60)
	ds_write_b32 v6, v23 offset:792
	s_waitcnt vmcnt(59)
	ds_write_b32 v6, v24 offset:1056
	s_waitcnt vmcnt(58)
	ds_write_b32 v6, v25 offset:1320
	s_waitcnt vmcnt(57)
	ds_write_b32 v6, v26 offset:1584
	s_waitcnt vmcnt(56)
	ds_write_b32 v6, v27 offset:1848
	s_waitcnt vmcnt(55)
	ds_write_b32 v6, v28 offset:2112
	s_waitcnt vmcnt(54)
	ds_write_b32 v6, v29 offset:2376
	s_waitcnt vmcnt(53)
	ds_write_b32 v6, v30 offset:2640
	s_waitcnt vmcnt(52)
	ds_write_b32 v6, v31 offset:2904
	s_waitcnt vmcnt(51)
	ds_write_b32 v6, v32 offset:3168
	s_waitcnt vmcnt(50)
	ds_write_b32 v6, v33 offset:3432
	s_waitcnt vmcnt(49)
	ds_write_b32 v6, v34 offset:3696
	s_waitcnt vmcnt(48)
	ds_write_b32 v6, v35 offset:3960
	s_waitcnt vmcnt(47)
	ds_write_b32 v6, v36 offset:4224
	s_waitcnt vmcnt(46)
	ds_write_b32 v6, v37 offset:4488
	s_waitcnt vmcnt(45)
	ds_write_b32 v6, v38 offset:4752
	s_waitcnt vmcnt(44)
	ds_write_b32 v6, v39 offset:5016
	s_waitcnt vmcnt(43)
	ds_write_b32 v6, v40 offset:5280
	s_waitcnt vmcnt(42)
	ds_write_b32 v6, v41 offset:5544
	s_waitcnt vmcnt(41)
	ds_write_b32 v6, v42 offset:5808
	s_waitcnt vmcnt(40)
	ds_write_b32 v6, v43 offset:6072
	s_waitcnt vmcnt(39)
	ds_write_b32 v6, v44 offset:6336
	s_waitcnt vmcnt(38)
	ds_write_b32 v6, v45 offset:6600
	s_waitcnt vmcnt(37)
	ds_write_b32 v6, v46 offset:6864
	s_waitcnt vmcnt(36)
	ds_write_b32 v6, v47 offset:7128
	s_waitcnt vmcnt(35)
	ds_write_b32 v6, v48 offset:7392
	s_waitcnt vmcnt(34)
	ds_write_b32 v6, v49 offset:7656
	s_waitcnt vmcnt(33)
	ds_write_b32 v6, v50 offset:7920
	s_waitcnt vmcnt(32)
	ds_write_b32 v6, v51 offset:8184
	s_waitcnt lgkmcnt(0)
	ds_read2_b32 v[60:61], v9 offset0:0 offset1:33
	ds_read2_b32 v[62:63], v9 offset0:66 offset1:99
	ds_read2_b32 v[64:65], v9 offset0:132 offset1:165
	ds_read2_b32 v[66:67], v9 offset0:198 offset1:231
	ds_read2_b32 v[68:69], v9 offset0:8 offset1:41
	ds_read2_b32 v[70:71], v9 offset0:74 offset1:107
	ds_read2_b32 v[72:73], v9 offset0:140 offset1:173
	ds_read2_b32 v[74:75], v9 offset0:206 offset1:239
	ds_read2_b32 v[76:77], v9 offset0:16 offset1:49
	ds_read2_b32 v[78:79], v9 offset0:82 offset1:115
	ds_read2_b32 v[80:81], v9 offset0:148 offset1:181
	ds_read2_b32 v[82:83], v9 offset0:214 offset1:247
	ds_read2_b32 v[84:85], v9 offset0:24 offset1:57
	ds_read2_b32 v[86:87], v9 offset0:90 offset1:123
	ds_read2_b32 v[88:89], v9 offset0:156 offset1:189
	ds_read2_b32 v[90:91], v9 offset0:222 offset1:255
	s_waitcnt lgkmcnt(12)
	v_cvt_pk_bf16_f32 v92, v60, v61
	v_cvt_pk_bf16_f32 v93, v62, v63
	v_cvt_pk_bf16_f32 v94, v64, v65
	v_cvt_pk_bf16_f32 v95, v66, v67
	global_store_dwordx4 v12, v[92:95], s[64:65]
	s_waitcnt lgkmcnt(8)
	v_cvt_pk_bf16_f32 v96, v68, v69
	v_cvt_pk_bf16_f32 v97, v70, v71
	v_cvt_pk_bf16_f32 v98, v72, v73
	v_cvt_pk_bf16_f32 v99, v74, v75
	global_store_dwordx4 v13, v[96:99], s[64:65]
	s_waitcnt lgkmcnt(4)
	v_cvt_pk_bf16_f32 v100, v76, v77
	v_cvt_pk_bf16_f32 v101, v78, v79
	v_cvt_pk_bf16_f32 v102, v80, v81
	v_cvt_pk_bf16_f32 v103, v82, v83
	global_store_dwordx4 v14, v[100:103], s[64:65]
	s_waitcnt lgkmcnt(0)
	v_cvt_pk_bf16_f32 v104, v84, v85
	v_cvt_pk_bf16_f32 v105, v86, v87
	v_cvt_pk_bf16_f32 v106, v88, v89
	v_cvt_pk_bf16_f32 v107, v90, v91
	global_store_dwordx4 v15, v[104:107], s[64:65]
	s_cmpk_lt_i32 s32, 0x1600
	s_cbranch_scc0 .Lxpf0p3e_fin
	s_add_i32 s59, s32, 0x800
	s_cmpk_lt_i32 s59, 0x1600
	s_cbranch_scc0 .Lxpf0p3e_dumA
	s_lshr_b32 s64, s59, 6
	s_and_b32 s65, s59, 63
	s_mul_i32 s66, s64, 0x80000
	s_lshl_b32 s67, s65, 7
	s_add_i32 s66, s66, s67
	s_add_u32 s66, s60, s66
	s_addc_u32 s67, s61, 0
	v_mov_b32_e32 v11, v5
	global_load_dword v20, v11, s[66:67] nt
	v_add_u32_e32 v11, 0x4000, v11
	global_load_dword v21, v11, s[66:67] nt
	v_add_u32_e32 v11, 0x4000, v11
	global_load_dword v22, v11, s[66:67] nt
	v_add_u32_e32 v11, 0x4000, v11
	global_load_dword v23, v11, s[66:67] nt
	v_add_u32_e32 v11, 0x4000, v11
	global_load_dword v24, v11, s[66:67] nt
	v_add_u32_e32 v11, 0x4000, v11
	global_load_dword v25, v11, s[66:67] nt
	v_add_u32_e32 v11, 0x4000, v11
	global_load_dword v26, v11, s[66:67] nt
	v_add_u32_e32 v11, 0x4000, v11
	global_load_dword v27, v11, s[66:67] nt
	v_add_u32_e32 v11, 0x4000, v11
	global_load_dword v28, v11, s[66:67] nt
	v_add_u32_e32 v11, 0x4000, v11
	global_load_dword v29, v11, s[66:67] nt
	v_add_u32_e32 v11, 0x4000, v11
	global_load_dword v30, v11, s[66:67] nt
	v_add_u32_e32 v11, 0x4000, v11
	global_load_dword v31, v11, s[66:67] nt
	v_add_u32_e32 v11, 0x4000, v11
	global_load_dword v32, v11, s[66:67] nt
	v_add_u32_e32 v11, 0x4000, v11
	global_load_dword v33, v11, s[66:67] nt
	v_add_u32_e32 v11, 0x4000, v11
	global_load_dword v34, v11, s[66:67] nt
	v_add_u32_e32 v11, 0x4000, v11
	global_load_dword v35, v11, s[66:67] nt
	v_add_u32_e32 v11, 0x4000, v11
	global_load_dword v36, v11, s[66:67] nt
	v_add_u32_e32 v11, 0x4000, v11
	global_load_dword v37, v11, s[66:67] nt
	v_add_u32_e32 v11, 0x4000, v11
	global_load_dword v38, v11, s[66:67] nt
	v_add_u32_e32 v11, 0x4000, v11
	global_load_dword v39, v11, s[66:67] nt
	v_add_u32_e32 v11, 0x4000, v11
	global_load_dword v40, v11, s[66:67] nt
	v_add_u32_e32 v11, 0x4000, v11
	global_load_dword v41, v11, s[66:67] nt
	v_add_u32_e32 v11, 0x4000, v11
	global_load_dword v42, v11, s[66:67] nt
	v_add_u32_e32 v11, 0x4000, v11
	global_load_dword v43, v11, s[66:67] nt
	v_add_u32_e32 v11, 0x4000, v11
	global_load_dword v44, v11, s[66:67] nt
	v_add_u32_e32 v11, 0x4000, v11
	global_load_dword v45, v11, s[66:67] nt
	v_add_u32_e32 v11, 0x4000, v11
	global_load_dword v46, v11, s[66:67] nt
	v_add_u32_e32 v11, 0x4000, v11
	global_load_dword v47, v11, s[66:67] nt
	v_add_u32_e32 v11, 0x4000, v11
	global_load_dword v48, v11, s[66:67] nt
	v_add_u32_e32 v11, 0x4000, v11
	global_load_dword v49, v11, s[66:67] nt
	v_add_u32_e32 v11, 0x4000, v11
	global_load_dword v50, v11, s[66:67] nt
	v_add_u32_e32 v11, 0x4000, v11
	global_load_dword v51, v11, s[66:67] nt
	s_branch .Lxpf0p3e_procB

; #define LAS __attribute__((address_space(3)))
; __device__ __forceinline__ void xpose_item(const float* src, int ld, bf16_t* dst, int K, int k0, LAS float* scr, int lane, const float* gk) {
;     if (src) {
; #pragma unroll 8
;         for (int i = 0; i < 32; ++i) { const int kk = 2 * i + (lane >> 5); scr[kk * 33 + (lane & 31)] = __builtin_nontemporal_load(src + (size_t)(k0 + kk) * ld + (lane & 31)); }
;     } else {
; #pragma unroll 8
;         for (int i = 0; i < 32; ++i) { const int kk = 2 * i + (lane >> 5); scr[kk * 33 + (lane & 31)] = 0.f; }
;     }
;     const int c = lane & 7;
;     f32x4 g0 = (f32x4){1.f, 1.f, 1.f, 1.f}, g1 = g0;
;     if (gk) { g0 = *(const f32x4*)(gk + k0 + 8 * c); g1 = *(const f32x4*)(gk + k0 + 8 * c + 4); }
; __global__ void __launch_bounds__(512) mega(Args a_byval) {
;     ...
;             it = xpose_all(a.in[27] + (size_t)lyr * D * D, nullptr, 2048, 2048, 2048, 2048, 0, (bf16_t*)(ws + (lyr ? WS_W_PG1 : WS_W_PG)), it, NGW, scr, lane, norm_ple_g + lyr * D);
.Lxpf0p3e_end:
	s_sub_i32 s59, s59, 0x1600
	s_cmpk_ge_i32 s59, 0x800
	s_cbranch_scc1 .Lxpq0p3e_end
	s_load_dwordx2 s[60:61], s[92:93], 0xd8
	s_load_dwordx2 s[62:63], s[92:93], 0xe8
	s_load_dwordx2 s[64:65], s[92:93], 0x20
	v_mov_b32_e32 v5, 0x2000
	v_mul_u32_u24_e32 v5, v3, v5
	v_add_u32_e32 v5, v5, v4
	v_mov_b32_e32 v10, 0x1000
	v_mul_u32_u24_e32 v10, v8, v10
	v_lshl_add_u32 v12, v7, 4, v10
	v_add_u32_e32 v13, 0x8000, v12
	v_add_u32_e32 v14, 0x10000, v12
	v_add_u32_e32 v15, 0x18000, v12
	s_waitcnt lgkmcnt(0)
	s_add_u32 s62, s62, 0x7b00000
	s_addc_u32 s63, s63, 0
	s_add_u32 s64, s64, 0x0
	s_addc_u32 s65, s65, 0
	v_lshlrev_b32_e32 v16, 5, v7
	v_mov_b32_e32 v17, v0
	v_lshl_add_u64 v[16:17], s[64:65], 0, v[16:17]
	s_lshr_b32 s64, s59, 6
	s_and_b32 s65, s59, 63
	s_mul_i32 s66, s64, 0x80000
	s_lshl_b32 s67, s65, 7
	s_add_i32 s66, s66, s67
	s_add_u32 s66, s60, s66
	s_addc_u32 s67, s61, 0
	s_lshl_b32 s64, s64, 8
	s_mov_b32 s65, 0
	v_lshl_add_u64 v[18:19], s[64:65], 0, v[16:17]
	global_load_dwordx4 v[52:55], v[18:19], off
	global_load_dwordx4 v[56:59], v[18:19], off offset:16
	v_mov_b32_e32 v11, v5
	global_load_dword v20, v11, s[66:67] nt
	v_add_u32_e32 v11, 0x4000, v11
	global_load_dword v21, v11, s[66:67] nt
	v_add_u32_e32 v11, 0x4000, v11
	global_load_dword v22, v11, s[66:67] nt
	v_add_u32_e32 v11, 0x4000, v11
	global_load_dword v23, v11, s[66:67] nt
	v_add_u32_e32 v11, 0x4000, v11
	global_load_dword v24, v11, s[66:67] nt
	v_add_u32_e32 v11, 0x4000, v11
	global_load_dword v25, v11, s[66:67] nt
	v_add_u32_e32 v11, 0x4000, v11
	global_load_dword v26, v11, s[66:67] nt
	v_add_u32_e32 v11, 0x4000, v11
	global_load_dword v27, v11, s[66:67] nt
	v_add_u32_e32 v11, 0x4000, v11
	global_load_dword v28, v11, s[66:67] nt
	v_add_u32_e32 v11, 0x4000, v11
	global_load_dword v29, v11, s[66:67] nt
	v_add_u32_e32 v11, 0x4000, v11
	global_load_dword v30, v11, s[66:67] nt
	v_add_u32_e32 v11, 0x4000, v11
	global_load_dword v31, v11, s[66:67] nt
	v_add_u32_e32 v11, 0x4000, v11
	global_load_dword v32, v11, s[66:67] nt
	v_add_u32_e32 v11, 0x4000, v11
	global_load_dword v33, v11, s[66:67] nt
	v_add_u32_e32 v11, 0x4000, v11
	global_load_dword v34, v11, s[66:67] nt
	v_add_u32_e32 v11, 0x4000, v11
	global_load_dword v35, v11, s[66:67] nt
	v_add_u32_e32 v11, 0x4000, v11
	global_load_dword v36, v11, s[66:67] nt
	v_add_u32_e32 v11, 0x4000, v11
	global_load_dword v37, v11, s[66:67] nt
	v_add_u32_e32 v11, 0x4000, v11
	global_load_dword v38, v11, s[66:67] nt
	v_add_u32_e32 v11, 0x4000, v11
	global_load_dword v39, v11, s[66:67] nt
	v_add_u32_e32 v11, 0x4000, v11
	global_load_dword v40, v11, s[66:67] nt
	v_add_u32_e32 v11, 0x4000, v11
	global_load_dword v41, v11, s[66:67] nt
	v_add_u32_e32 v11, 0x4000, v11
	global_load_dword v42, v11, s[66:67] nt
	v_add_u32_e32 v11, 0x4000, v11
	global_load_dword v43, v11, s[66:67] nt
	v_add_u32_e32 v11, 0x4000, v11
	global_load_dword v44, v11, s[66:67] nt
	v_add_u32_e32 v11, 0x4000, v11
	global_load_dword v45, v11, s[66:67] nt
	v_add_u32_e32 v11, 0x4000, v11
	global_load_dword v46, v11, s[66:67] nt
	v_add_u32_e32 v11, 0x4000, v11
	global_load_dword v47, v11, s[66:67] nt
	v_add_u32_e32 v11, 0x4000, v11
	global_load_dword v48, v11, s[66:67] nt
	v_add_u32_e32 v11, 0x4000, v11
	global_load_dword v49, v11, s[66:67] nt
	v_add_u32_e32 v11, 0x4000, v11
	global_load_dword v50, v11, s[66:67] nt
	v_add_u32_e32 v11, 0x4000, v11
	global_load_dword v51, v11, s[66:67] nt
.Lxpq0p3e_loop:
	s_add_i32 s32, s59, 0x800
	s_cmpk_lt_i32 s32, 0x800
	s_cbranch_scc0 .Lxpq0p3e_dumB
	s_lshr_b32 s64, s32, 6
	s_and_b32 s65, s32, 63
	s_mul_i32 s66, s64, 0x80000
	s_lshl_b32 s67, s65, 7
	s_add_i32 s66, s66, s67
	s_add_u32 s66, s60, s66
	s_addc_u32 s67, s61, 0
	s_lshl_b32 s64, s64, 8
	s_mov_b32 s65, 0
	v_lshl_add_u64 v[18:19], s[64:65], 0, v[16:17]
	global_load_dwordx4 v[160:163], v[18:19], off
	global_load_dwordx4 v[164:167], v[18:19], off offset:16
	v_mov_b32_e32 v11, v5
	global_load_dword v108, v11, s[66:67] nt
	v_add_u32_e32 v11, 0x4000, v11
	global_load_dword v109, v11, s[66:67] nt
	v_add_u32_e32 v11, 0x4000, v11
	global_load_dword v110, v11, s[66:67] nt
	v_add_u32_e32 v11, 0x4000, v11
	global_load_dword v111, v11, s[66:67] nt
	v_add_u32_e32 v11, 0x4000, v11
	global_load_dword v112, v11, s[66:67] nt
	v_add_u32_e32 v11, 0x4000, v11
	global_load_dword v113, v11, s[66:67] nt
	v_add_u32_e32 v11, 0x4000, v11
	global_load_dword v114, v11, s[66:67] nt
	v_add_u32_e32 v11, 0x4000, v11
	global_load_dword v115, v11, s[66:67] nt
	v_add_u32_e32 v11, 0x4000, v11
	global_load_dword v116, v11, s[66:67] nt
	v_add_u32_e32 v11, 0x4000, v11
	global_load_dword v117, v11, s[66:67] nt
	v_add_u32_e32 v11, 0x4000, v11
	global_load_dword v118, v11, s[66:67] nt
	v_add_u32_e32 v11, 0x4000, v11
	global_load_dword v119, v11, s[66:67] nt
	v_add_u32_e32 v11, 0x4000, v11
	global_load_dword v120, v11, s[66:67] nt
	v_add_u32_e32 v11, 0x4000, v11
	global_load_dword v121, v11, s[66:67] nt
	v_add_u32_e32 v11, 0x4000, v11
	global_load_dword v122, v11, s[66:67] nt
	v_add_u32_e32 v11, 0x4000, v11
	global_load_dword v123, v11, s[66:67] nt
	v_add_u32_e32 v11, 0x4000, v11
	global_load_dword v124, v11, s[66:67] nt
	v_add_u32_e32 v11, 0x4000, v11
	global_load_dword v125, v11, s[66:67] nt
	v_add_u32_e32 v11, 0x4000, v11
	global_load_dword v126, v11, s[66:67] nt
	v_add_u32_e32 v11, 0x4000, v11
	global_load_dword v127, v11, s[66:67] nt
	v_add_u32_e32 v11, 0x4000, v11
	global_load_dword v128, v11, s[66:67] nt
	v_add_u32_e32 v11, 0x4000, v11
	global_load_dword v129, v11, s[66:67] nt
	v_add_u32_e32 v11, 0x4000, v11
	global_load_dword v130, v11, s[66:67] nt
	v_add_u32_e32 v11, 0x4000, v11
	global_load_dword v131, v11, s[66:67] nt
	v_add_u32_e32 v11, 0x4000, v11
	global_load_dword v132, v11, s[66:67] nt
	v_add_u32_e32 v11, 0x4000, v11
	global_load_dword v133, v11, s[66:67] nt
	v_add_u32_e32 v11, 0x4000, v11
	global_load_dword v134, v11, s[66:67] nt
	v_add_u32_e32 v11, 0x4000, v11
	global_load_dword v135, v11, s[66:67] nt
	v_add_u32_e32 v11, 0x4000, v11
	global_load_dword v136, v11, s[66:67] nt
	v_add_u32_e32 v11, 0x4000, v11
	global_load_dword v137, v11, s[66:67] nt
	v_add_u32_e32 v11, 0x4000, v11
	global_load_dword v138, v11, s[66:67] nt
	v_add_u32_e32 v11, 0x4000, v11
	global_load_dword v139, v11, s[66:67] nt
	s_branch .Lxpq0p3e_procA

; #define LAS __attribute__((address_space(3)))
; __device__ __forceinline__ unsigned cvt_pk_bf16(float lo, float hi) { unsigned r; asm volatile("v_cvt_pk_bf16_f32 %0, %1, %2" : "=v"(r) : "v"(lo), "v"(hi)); return r; }
; __device__ __forceinline__ void xpose_item(const float* src, int ld, bf16_t* dst, int K, int k0, LAS float* scr, int lane, const float* gk) {
;     ...
;         for (int i = 0; i < 32; ++i) { const int kk = 2 * i + (lane >> 5); scr[kk * 33 + (lane & 31)] = __builtin_nontemporal_load(src + (size_t)(k0 + kk) * ld + (lane & 31)); }
;     } else {
; #pragma unroll 8
;         for (int i = 0; i < 32; ++i) { const int kk = 2 * i + (lane >> 5); scr[kk * 33 + (lane & 31)] = 0.f; }
;     }
;     const int c = lane & 7;
;     f32x4 g0 = (f32x4){1.f, 1.f, 1.f, 1.f}, g1 = g0;
;     if (gk) { g0 = *(const f32x4*)(gk + k0 + 8 * c); g1 = *(const f32x4*)(gk + k0 + 8 * c + 4); }
;     asm volatile("s_waitcnt lgkmcnt(0)" ::: "memory");
; #pragma unroll
;     for (int j = 0; j < 4; ++j) { const int n = (lane >> 3) + 8 * j; const LAS float* s = scr + (8 * c) * 33 + n;
;         u32x4 o; o.x = cvt_pk_bf16(s[0 * 33] * g0[0], s[1 * 33] * g0[1]); o.y = cvt_pk_bf16(s[2 * 33] * g0[2], s[3 * 33] * g0[3]); o.z = cvt_pk_bf16(s[4 * 33] * g1[0], s[5 * 33] * g1[1]); o.w = cvt_pk_bf16(s[6 * 33] * g1[2], s[7 * 33] * g1[3]);
;         *(u32x4*)(dst + (size_t)n * K + k0 + 8 * c) = o; }
.Lxpq0p3e_procA:
	s_lshr_b32 s64, s59, 6
	s_and_b32 s65, s59, 63
	s_mul_i32 s68, s65, 0x20000
	s_lshl_b32 s64, s64, 7
	s_add_i32 s68, s68, s64
	s_add_u32 s64, s62, s68
	s_addc_u32 s65, s63, 0
	s_waitcnt vmcnt(63)
	ds_write_b32 v6, v20 offset:0
	s_waitcnt vmcnt(62)
	ds_write_b32 v6, v21 offset:264
	s_waitcnt vmcnt(61)
	ds_write_b32 v6, v22 offset:528
	s_waitcnt vmcnt(60)
	ds_write_b32 v6, v23 offset:792
	s_waitcnt vmcnt(59)
	ds_write_b32 v6, v24 offset:1056
	s_waitcnt vmcnt(58)
	ds_write_b32 v6, v25 offset:1320
	s_waitcnt vmcnt(57)
	ds_write_b32 v6, v26 offset:1584
	s_waitcnt vmcnt(56)
	ds_write_b32 v6, v27 offset:1848
	s_waitcnt vmcnt(55)
	ds_write_b32 v6, v28 offset:2112
	s_waitcnt vmcnt(54)
	ds_write_b32 v6, v29 offset:2376
	s_waitcnt vmcnt(53)
	ds_write_b32 v6, v30 offset:2640
	s_waitcnt vmcnt(52)
	ds_write_b32 v6, v31 offset:2904
	s_waitcnt vmcnt(51)
	ds_write_b32 v6, v32 offset:3168
	s_waitcnt vmcnt(50)
	ds_write_b32 v6, v33 offset:3432
	s_waitcnt vmcnt(49)
	ds_write_b32 v6, v34 offset:3696
	s_waitcnt vmcnt(48)
	ds_write_b32 v6, v35 offset:3960
	s_waitcnt vmcnt(47)
	ds_write_b32 v6, v36 offset:4224
	s_waitcnt vmcnt(46)
	ds_write_b32 v6, v37 offset:4488
	s_waitcnt vmcnt(45)
	ds_write_b32 v6, v38 offset:4752
	s_waitcnt vmcnt(44)
	ds_write_b32 v6, v39 offset:5016
	s_waitcnt vmcnt(43)
	ds_write_b32 v6, v40 offset:5280
	s_waitcnt vmcnt(42)
	ds_write_b32 v6, v41 offset:5544
	s_waitcnt vmcnt(41)
	ds_write_b32 v6, v42 offset:5808
	s_waitcnt vmcnt(40)
	ds_write_b32 v6, v43 offset:6072
	s_waitcnt vmcnt(39)
	ds_write_b32 v6, v44 offset:6336
	s_waitcnt vmcnt(38)
	ds_write_b32 v6, v45 offset:6600
	s_waitcnt vmcnt(37)
	ds_write_b32 v6, v46 offset:6864
	s_waitcnt vmcnt(36)
	ds_write_b32 v6, v47 offset:7128
	s_waitcnt vmcnt(35)
	ds_write_b32 v6, v48 offset:7392
	s_waitcnt vmcnt(34)
	ds_write_b32 v6, v49 offset:7656
	s_waitcnt vmcnt(33)
	ds_write_b32 v6, v50 offset:7920
	s_waitcnt vmcnt(32)
	ds_write_b32 v6, v51 offset:8184
	s_waitcnt lgkmcnt(0)
	ds_read2_b32 v[60:61], v9 offset0:0 offset1:33
	ds_read2_b32 v[62:63], v9 offset0:66 offset1:99
	ds_read2_b32 v[64:65], v9 offset0:132 offset1:165
	ds_read2_b32 v[66:67], v9 offset0:198 offset1:231
	ds_read2_b32 v[68:69], v9 offset0:8 offset1:41
	ds_read2_b32 v[70:71], v9 offset0:74 offset1:107
	ds_read2_b32 v[72:73], v9 offset0:140 offset1:173
	ds_read2_b32 v[74:75], v9 offset0:206 offset1:239
	ds_read2_b32 v[76:77], v9 offset0:16 offset1:49
	ds_read2_b32 v[78:79], v9 offset0:82 offset1:115
	ds_read2_b32 v[80:81], v9 offset0:148 offset1:181
	ds_read2_b32 v[82:83], v9 offset0:214 offset1:247
	ds_read2_b32 v[84:85], v9 offset0:24 offset1:57
	ds_read2_b32 v[86:87], v9 offset0:90 offset1:123
	ds_read2_b32 v[88:89], v9 offset0:156 offset1:189
	ds_read2_b32 v[90:91], v9 offset0:222 offset1:255
	s_waitcnt lgkmcnt(12)
	v_mul_f32_e32 v60, v60, v52
	v_mul_f32_e32 v61, v61, v53
	v_mul_f32_e32 v62, v62, v54
	v_mul_f32_e32 v63, v63, v55
	v_mul_f32_e32 v64, v64, v56
	v_mul_f32_e32 v65, v65, v57
	v_mul_f32_e32 v66, v66, v58
	v_mul_f32_e32 v67, v67, v59
	v_cvt_pk_bf16_f32 v92, v60, v61
	v_cvt_pk_bf16_f32 v93, v62, v63
	v_cvt_pk_bf16_f32 v94, v64, v65
	v_cvt_pk_bf16_f32 v95, v66, v67
	global_store_dwordx4 v12, v[92:95], s[64:65]
	s_waitcnt lgkmcnt(8)
	v_mul_f32_e32 v68, v68, v52
	v_mul_f32_e32 v69, v69, v53
	v_mul_f32_e32 v70, v70, v54
	v_mul_f32_e32 v71, v71, v55
	v_mul_f32_e32 v72, v72, v56
	v_mul_f32_e32 v73, v73, v57
	v_mul_f32_e32 v74, v74, v58
	v_mul_f32_e32 v75, v75, v59
	v_cvt_pk_bf16_f32 v96, v68, v69
	v_cvt_pk_bf16_f32 v97, v70, v71
	v_cvt_pk_bf16_f32 v98, v72, v73
	v_cvt_pk_bf16_f32 v99, v74, v75
	global_store_dwordx4 v13, v[96:99], s[64:65]
	s_waitcnt lgkmcnt(4)
	v_mul_f32_e32 v76, v76, v52
	v_mul_f32_e32 v77, v77, v53
	v_mul_f32_e32 v78, v78, v54
	v_mul_f32_e32 v79, v79, v55
	v_mul_f32_e32 v80, v80, v56
	v_mul_f32_e32 v81, v81, v57
	v_mul_f32_e32 v82, v82, v58
	v_mul_f32_e32 v83, v83, v59
	v_cvt_pk_bf16_f32 v100, v76, v77
	v_cvt_pk_bf16_f32 v101, v78, v79
	v_cvt_pk_bf16_f32 v102, v80, v81
	v_cvt_pk_bf16_f32 v103, v82, v83
	global_store_dwordx4 v14, v[100:103], s[64:65]
	s_waitcnt lgkmcnt(0)
	v_mul_f32_e32 v84, v84, v52
	v_mul_f32_e32 v85, v85, v53
	v_mul_f32_e32 v86, v86, v54
	v_mul_f32_e32 v87, v87, v55
	v_mul_f32_e32 v88, v88, v56
	v_mul_f32_e32 v89, v89, v57
	v_mul_f32_e32 v90, v90, v58
	v_mul_f32_e32 v91, v91, v59
	v_cvt_pk_bf16_f32 v104, v84, v85
	v_cvt_pk_bf16_f32 v105, v86, v87
	v_cvt_pk_bf16_f32 v106, v88, v89
	v_cvt_pk_bf16_f32 v107, v90, v91
	global_store_dwordx4 v15, v[104:107], s[64:65]
	s_cmpk_lt_i32 s32, 0x800
	s_cbranch_scc0 .Lxpq0p3e_fin
; #define LAS __attribute__((address_space(3)))
; __device__ __forceinline__ void xpose_item(const float* src, int ld, bf16_t* dst, int K, int k0, LAS float* scr, int lane, const float* gk) {
;     if (src) {
; #pragma unroll 8
;         for (int i = 0; i < 32; ++i) { const int kk = 2 * i + (lane >> 5); scr[kk * 33 + (lane & 31)] = __builtin_nontemporal_load(src + (size_t)(k0 + kk) * ld + (lane & 31)); }
;     } else {
; #pragma unroll 8
;         for (int i = 0; i < 32; ++i) { const int kk = 2 * i + (lane >> 5); scr[kk * 33 + (lane & 31)] = 0.f; }
;     }
;     const int c = lane & 7;
;     f32x4 g0 = (f32x4){1.f, 1.f, 1.f, 1.f}, g1 = g0;
;     if (gk) { g0 = *(const f32x4*)(gk + k0 + 8 * c); g1 = *(const f32x4*)(gk + k0 + 8 * c + 4); }
	s_add_i32 s59, s32, 0x800
	s_cmpk_lt_i32 s59, 0x800
	s_cbranch_scc0 .Lxpq0p3e_dumA
	s_lshr_b32 s64, s59, 6
	s_and_b32 s65, s59, 63
	s_mul_i32 s66, s64, 0x80000
	s_lshl_b32 s67, s65, 7
	s_add_i32 s66, s66, s67
	s_add_u32 s66, s60, s66
	s_addc_u32 s67, s61, 0
	s_lshl_b32 s64, s64, 8
	s_mov_b32 s65, 0
	v_lshl_add_u64 v[18:19], s[64:65], 0, v[16:17]
	global_load_dwordx4 v[52:55], v[18:19], off
	global_load_dwordx4 v[56:59], v[18:19], off offset:16
	v_mov_b32_e32 v11, v5
	global_load_dword v20, v11, s[66:67] nt
	v_add_u32_e32 v11, 0x4000, v11
	global_load_dword v21, v11, s[66:67] nt
	v_add_u32_e32 v11, 0x4000, v11
	global_load_dword v22, v11, s[66:67] nt
	v_add_u32_e32 v11, 0x4000, v11
	global_load_dword v23, v11, s[66:67] nt
	v_add_u32_e32 v11, 0x4000, v11
	global_load_dword v24, v11, s[66:67] nt
	v_add_u32_e32 v11, 0x4000, v11
	global_load_dword v25, v11, s[66:67] nt
	v_add_u32_e32 v11, 0x4000, v11
	global_load_dword v26, v11, s[66:67] nt
	v_add_u32_e32 v11, 0x4000, v11
	global_load_dword v27, v11, s[66:67] nt
	v_add_u32_e32 v11, 0x4000, v11
	global_load_dword v28, v11, s[66:67] nt
	v_add_u32_e32 v11, 0x4000, v11
	global_load_dword v29, v11, s[66:67] nt
	v_add_u32_e32 v11, 0x4000, v11
	global_load_dword v30, v11, s[66:67] nt
	v_add_u32_e32 v11, 0x4000, v11
	global_load_dword v31, v11, s[66:67] nt
	v_add_u32_e32 v11, 0x4000, v11
	global_load_dword v32, v11, s[66:67] nt
	v_add_u32_e32 v11, 0x4000, v11
	global_load_dword v33, v11, s[66:67] nt
	v_add_u32_e32 v11, 0x4000, v11
	global_load_dword v34, v11, s[66:67] nt
	v_add_u32_e32 v11, 0x4000, v11
	global_load_dword v35, v11, s[66:67] nt
	v_add_u32_e32 v11, 0x4000, v11
	global_load_dword v36, v11, s[66:67] nt
	v_add_u32_e32 v11, 0x4000, v11
	global_load_dword v37, v11, s[66:67] nt
	v_add_u32_e32 v11, 0x4000, v11
	global_load_dword v38, v11, s[66:67] nt
	v_add_u32_e32 v11, 0x4000, v11
	global_load_dword v39, v11, s[66:67] nt
	v_add_u32_e32 v11, 0x4000, v11
	global_load_dword v40, v11, s[66:67] nt
	v_add_u32_e32 v11, 0x4000, v11
	global_load_dword v41, v11, s[66:67] nt
	v_add_u32_e32 v11, 0x4000, v11
	global_load_dword v42, v11, s[66:67] nt
	v_add_u32_e32 v11, 0x4000, v11
	global_load_dword v43, v11, s[66:67] nt
	v_add_u32_e32 v11, 0x4000, v11
	global_load_dword v44, v11, s[66:67] nt
	v_add_u32_e32 v11, 0x4000, v11
	global_load_dword v45, v11, s[66:67] nt
	v_add_u32_e32 v11, 0x4000, v11
	global_load_dword v46, v11, s[66:67] nt
	v_add_u32_e32 v11, 0x4000, v11
	global_load_dword v47, v11, s[66:67] nt
	v_add_u32_e32 v11, 0x4000, v11
	global_load_dword v48, v11, s[66:67] nt
	v_add_u32_e32 v11, 0x4000, v11
	global_load_dword v49, v11, s[66:67] nt
	v_add_u32_e32 v11, 0x4000, v11
	global_load_dword v50, v11, s[66:67] nt
	v_add_u32_e32 v11, 0x4000, v11
	global_load_dword v51, v11, s[66:67] nt
	s_branch .Lxpq0p3e_procB

; #define LAS __attribute__((address_space(3)))
; __device__ __forceinline__ void xpose_item(const float* src, int ld, bf16_t* dst, int K, int k0, LAS float* scr, int lane, const float* gk) {
;     if (src) {
; #pragma unroll 8
;         for (int i = 0; i < 32; ++i) { const int kk = 2 * i + (lane >> 5); scr[kk * 33 + (lane & 31)] = __builtin_nontemporal_load(src + (size_t)(k0 + kk) * ld + (lane & 31)); }
;     } else {
; #pragma unroll 8
;         for (int i = 0; i < 32; ++i) { const int kk = 2 * i + (lane >> 5); scr[kk * 33 + (lane & 31)] = 0.f; }
;     }
;     const int c = lane & 7;
;     f32x4 g0 = (f32x4){1.f, 1.f, 1.f, 1.f}, g1 = g0;
;     if (gk) { g0 = *(const f32x4*)(gk + k0 + 8 * c); g1 = *(const f32x4*)(gk + k0 + 8 * c + 4); }
; __global__ void __launch_bounds__(512) mega(Args a_byval) {
;     ...
;             it = xpose_all(a.in[26] + (size_t)lyr * PLE * D, nullptr, 2048, 256, 2048, 2048, 0, (bf16_t*)(ws + (lyr ? WS_W_PP1 : WS_W_PP)), it, NGW, scr, lane);
.Lxpq0p3e_end:
	s_sub_i32 s59, s59, 0x800
	s_cmpk_ge_i32 s59, 0x100
	s_cbranch_scc1 .Lxpr0p3e_end
	s_load_dwordx2 s[60:61], s[92:93], 0xd0
	s_load_dwordx2 s[62:63], s[92:93], 0xe8
	v_mov_b32_e32 v5, 0x2000
	v_mul_u32_u24_e32 v5, v3, v5
	v_add_u32_e32 v5, v5, v4
	v_mov_b32_e32 v10, 0x200
	v_mul_u32_u24_e32 v10, v8, v10
	v_lshl_add_u32 v12, v7, 4, v10
	v_add_u32_e32 v13, 0x1000, v12
	v_add_u32_e32 v14, 0x2000, v12
	v_add_u32_e32 v15, 0x3000, v12
	s_waitcnt lgkmcnt(0)
	s_add_u32 s62, s62, 0x8300000
	s_addc_u32 s63, s63, 0
	s_lshr_b32 s64, s59, 6
	s_and_b32 s65, s59, 63
	s_mul_i32 s66, s64, 0x80000
	s_lshl_b32 s67, s65, 7
	s_add_i32 s66, s66, s67
	s_add_u32 s66, s60, s66
	s_addc_u32 s67, s61, 0
	v_mov_b32_e32 v11, v5
	global_load_dword v20, v11, s[66:67] nt
	v_add_u32_e32 v11, 0x4000, v11
	global_load_dword v21, v11, s[66:67] nt
	v_add_u32_e32 v11, 0x4000, v11
	global_load_dword v22, v11, s[66:67] nt
	v_add_u32_e32 v11, 0x4000, v11
	global_load_dword v23, v11, s[66:67] nt
	v_add_u32_e32 v11, 0x4000, v11
	global_load_dword v24, v11, s[66:67] nt
	v_add_u32_e32 v11, 0x4000, v11
	global_load_dword v25, v11, s[66:67] nt
	v_add_u32_e32 v11, 0x4000, v11
	global_load_dword v26, v11, s[66:67] nt
	v_add_u32_e32 v11, 0x4000, v11
	global_load_dword v27, v11, s[66:67] nt
	v_add_u32_e32 v11, 0x4000, v11
	global_load_dword v28, v11, s[66:67] nt
	v_add_u32_e32 v11, 0x4000, v11
	global_load_dword v29, v11, s[66:67] nt
	v_add_u32_e32 v11, 0x4000, v11
	global_load_dword v30, v11, s[66:67] nt
	v_add_u32_e32 v11, 0x4000, v11
	global_load_dword v31, v11, s[66:67] nt
	v_add_u32_e32 v11, 0x4000, v11
	global_load_dword v32, v11, s[66:67] nt
	v_add_u32_e32 v11, 0x4000, v11
	global_load_dword v33, v11, s[66:67] nt
	v_add_u32_e32 v11, 0x4000, v11
	global_load_dword v34, v11, s[66:67] nt
	v_add_u32_e32 v11, 0x4000, v11
	global_load_dword v35, v11, s[66:67] nt
	v_add_u32_e32 v11, 0x4000, v11
	global_load_dword v36, v11, s[66:67] nt
	v_add_u32_e32 v11, 0x4000, v11
	global_load_dword v37, v11, s[66:67] nt
	v_add_u32_e32 v11, 0x4000, v11
	global_load_dword v38, v11, s[66:67] nt
	v_add_u32_e32 v11, 0x4000, v11
	global_load_dword v39, v11, s[66:67] nt
	v_add_u32_e32 v11, 0x4000, v11
	global_load_dword v40, v11, s[66:67] nt
	v_add_u32_e32 v11, 0x4000, v11
	global_load_dword v41, v11, s[66:67] nt
	v_add_u32_e32 v11, 0x4000, v11
	global_load_dword v42, v11, s[66:67] nt
	v_add_u32_e32 v11, 0x4000, v11
	global_load_dword v43, v11, s[66:67] nt
	v_add_u32_e32 v11, 0x4000, v11
	global_load_dword v44, v11, s[66:67] nt
	v_add_u32_e32 v11, 0x4000, v11
	global_load_dword v45, v11, s[66:67] nt
	v_add_u32_e32 v11, 0x4000, v11
	global_load_dword v46, v11, s[66:67] nt
	v_add_u32_e32 v11, 0x4000, v11
	global_load_dword v47, v11, s[66:67] nt
	v_add_u32_e32 v11, 0x4000, v11
	global_load_dword v48, v11, s[66:67] nt
	v_add_u32_e32 v11, 0x4000, v11
	global_load_dword v49, v11, s[66:67] nt
	v_add_u32_e32 v11, 0x4000, v11
	global_load_dword v50, v11, s[66:67] nt
	v_add_u32_e32 v11, 0x4000, v11
	global_load_dword v51, v11, s[66:67] nt
.Lxpr0p3e_loop:
	s_add_i32 s32, s59, 0x800
	s_cmpk_lt_i32 s32, 0x100
	s_cbranch_scc0 .Lxpr0p3e_dumB
	s_lshr_b32 s64, s32, 6
	s_and_b32 s65, s32, 63
	s_mul_i32 s66, s64, 0x80000
	s_lshl_b32 s67, s65, 7
	s_add_i32 s66, s66, s67
	s_add_u32 s66, s60, s66
	s_addc_u32 s67, s61, 0
	v_mov_b32_e32 v11, v5
	global_load_dword v108, v11, s[66:67] nt
	v_add_u32_e32 v11, 0x4000, v11
	global_load_dword v109, v11, s[66:67] nt
	v_add_u32_e32 v11, 0x4000, v11
	global_load_dword v110, v11, s[66:67] nt
	v_add_u32_e32 v11, 0x4000, v11
	global_load_dword v111, v11, s[66:67] nt
	v_add_u32_e32 v11, 0x4000, v11
	global_load_dword v112, v11, s[66:67] nt
	v_add_u32_e32 v11, 0x4000, v11
	global_load_dword v113, v11, s[66:67] nt
	v_add_u32_e32 v11, 0x4000, v11
	global_load_dword v114, v11, s[66:67] nt
	v_add_u32_e32 v11, 0x4000, v11
	global_load_dword v115, v11, s[66:67] nt
	v_add_u32_e32 v11, 0x4000, v11
	global_load_dword v116, v11, s[66:67] nt
	v_add_u32_e32 v11, 0x4000, v11
	global_load_dword v117, v11, s[66:67] nt
	v_add_u32_e32 v11, 0x4000, v11
	global_load_dword v118, v11, s[66:67] nt
	v_add_u32_e32 v11, 0x4000, v11
	global_load_dword v119, v11, s[66:67] nt
	v_add_u32_e32 v11, 0x4000, v11
	global_load_dword v120, v11, s[66:67] nt
	v_add_u32_e32 v11, 0x4000, v11
	global_load_dword v121, v11, s[66:67] nt
	v_add_u32_e32 v11, 0x4000, v11
	global_load_dword v122, v11, s[66:67] nt
	v_add_u32_e32 v11, 0x4000, v11
	global_load_dword v123, v11, s[66:67] nt
	v_add_u32_e32 v11, 0x4000, v11
	global_load_dword v124, v11, s[66:67] nt
	v_add_u32_e32 v11, 0x4000, v11
	global_load_dword v125, v11, s[66:67] nt
	v_add_u32_e32 v11, 0x4000, v11
	global_load_dword v126, v11, s[66:67] nt
	v_add_u32_e32 v11, 0x4000, v11
	global_load_dword v127, v11, s[66:67] nt
	v_add_u32_e32 v11, 0x4000, v11
	global_load_dword v128, v11, s[66:67] nt
	v_add_u32_e32 v11, 0x4000, v11
	global_load_dword v129, v11, s[66:67] nt
	v_add_u32_e32 v11, 0x4000, v11
	global_load_dword v130, v11, s[66:67] nt
	v_add_u32_e32 v11, 0x4000, v11
	global_load_dword v131, v11, s[66:67] nt
	v_add_u32_e32 v11, 0x4000, v11
	global_load_dword v132, v11, s[66:67] nt
	v_add_u32_e32 v11, 0x4000, v11
	global_load_dword v133, v11, s[66:67] nt
	v_add_u32_e32 v11, 0x4000, v11
	global_load_dword v134, v11, s[66:67] nt
	v_add_u32_e32 v11, 0x4000, v11
	global_load_dword v135, v11, s[66:67] nt
	v_add_u32_e32 v11, 0x4000, v11
	global_load_dword v136, v11, s[66:67] nt
	v_add_u32_e32 v11, 0x4000, v11
	global_load_dword v137, v11, s[66:67] nt
	v_add_u32_e32 v11, 0x4000, v11
	global_load_dword v138, v11, s[66:67] nt
	v_add_u32_e32 v11, 0x4000, v11
	global_load_dword v139, v11, s[66:67] nt
	s_branch .Lxpr0p3e_procA

; #define LAS __attribute__((address_space(3)))
; __device__ __forceinline__ unsigned cvt_pk_bf16(float lo, float hi) { unsigned r; asm volatile("v_cvt_pk_bf16_f32 %0, %1, %2" : "=v"(r) : "v"(lo), "v"(hi)); return r; }
; __device__ __forceinline__ void xpose_item(const float* src, int ld, bf16_t* dst, int K, int k0, LAS float* scr, int lane, const float* gk) {
;     ...
;         for (int i = 0; i < 32; ++i) { const int kk = 2 * i + (lane >> 5); scr[kk * 33 + (lane & 31)] = __builtin_nontemporal_load(src + (size_t)(k0 + kk) * ld + (lane & 31)); }
;     } else {
; #pragma unroll 8
;         for (int i = 0; i < 32; ++i) { const int kk = 2 * i + (lane >> 5); scr[kk * 33 + (lane & 31)] = 0.f; }
;     }
;     const int c = lane & 7;
;     f32x4 g0 = (f32x4){1.f, 1.f, 1.f, 1.f}, g1 = g0;
;     if (gk) { g0 = *(const f32x4*)(gk + k0 + 8 * c); g1 = *(const f32x4*)(gk + k0 + 8 * c + 4); }
;     asm volatile("s_waitcnt lgkmcnt(0)" ::: "memory");
; #pragma unroll
;     for (int j = 0; j < 4; ++j) { const int n = (lane >> 3) + 8 * j; const LAS float* s = scr + (8 * c) * 33 + n;
;         u32x4 o; o.x = cvt_pk_bf16(s[0 * 33] * g0[0], s[1 * 33] * g0[1]); o.y = cvt_pk_bf16(s[2 * 33] * g0[2], s[3 * 33] * g0[3]); o.z = cvt_pk_bf16(s[4 * 33] * g1[0], s[5 * 33] * g1[1]); o.w = cvt_pk_bf16(s[6 * 33] * g1[2], s[7 * 33] * g1[3]);
;         *(u32x4*)(dst + (size_t)n * K + k0 + 8 * c) = o; }
.Lxpr0p3e_procA:
	s_lshr_b32 s64, s59, 6
	s_and_b32 s65, s59, 63
	s_mul_i32 s68, s65, 0x4000
	s_lshl_b32 s64, s64, 7
	s_add_i32 s68, s68, s64
	s_add_u32 s64, s62, s68
	s_addc_u32 s65, s63, 0
	s_waitcnt vmcnt(63)
	ds_write_b32 v6, v20 offset:0
	s_waitcnt vmcnt(62)
	ds_write_b32 v6, v21 offset:264
	s_waitcnt vmcnt(61)
	ds_write_b32 v6, v22 offset:528
	s_waitcnt vmcnt(60)
	ds_write_b32 v6, v23 offset:792
	s_waitcnt vmcnt(59)
	ds_write_b32 v6, v24 offset:1056
	s_waitcnt vmcnt(58)
	ds_write_b32 v6, v25 offset:1320
	s_waitcnt vmcnt(57)
	ds_write_b32 v6, v26 offset:1584
	s_waitcnt vmcnt(56)
	ds_write_b32 v6, v27 offset:1848
	s_waitcnt vmcnt(55)
	ds_write_b32 v6, v28 offset:2112
	s_waitcnt vmcnt(54)
	ds_write_b32 v6, v29 offset:2376
	s_waitcnt vmcnt(53)
	ds_write_b32 v6, v30 offset:2640
	s_waitcnt vmcnt(52)
	ds_write_b32 v6, v31 offset:2904
	s_waitcnt vmcnt(51)
	ds_write_b32 v6, v32 offset:3168
	s_waitcnt vmcnt(50)
	ds_write_b32 v6, v33 offset:3432
	s_waitcnt vmcnt(49)
	ds_write_b32 v6, v34 offset:3696
	s_waitcnt vmcnt(48)
	ds_write_b32 v6, v35 offset:3960
	s_waitcnt vmcnt(47)
	ds_write_b32 v6, v36 offset:4224
	s_waitcnt vmcnt(46)
	ds_write_b32 v6, v37 offset:4488
	s_waitcnt vmcnt(45)
	ds_write_b32 v6, v38 offset:4752
	s_waitcnt vmcnt(44)
	ds_write_b32 v6, v39 offset:5016
	s_waitcnt vmcnt(43)
	ds_write_b32 v6, v40 offset:5280
	s_waitcnt vmcnt(42)
	ds_write_b32 v6, v41 offset:5544
	s_waitcnt vmcnt(41)
	ds_write_b32 v6, v42 offset:5808
	s_waitcnt vmcnt(40)
	ds_write_b32 v6, v43 offset:6072
	s_waitcnt vmcnt(39)
	ds_write_b32 v6, v44 offset:6336
	s_waitcnt vmcnt(38)
	ds_write_b32 v6, v45 offset:6600
	s_waitcnt vmcnt(37)
	ds_write_b32 v6, v46 offset:6864
	s_waitcnt vmcnt(36)
	ds_write_b32 v6, v47 offset:7128
	s_waitcnt vmcnt(35)
	ds_write_b32 v6, v48 offset:7392
	s_waitcnt vmcnt(34)
	ds_write_b32 v6, v49 offset:7656
	s_waitcnt vmcnt(33)
	ds_write_b32 v6, v50 offset:7920
	s_waitcnt vmcnt(32)
	ds_write_b32 v6, v51 offset:8184
	s_waitcnt lgkmcnt(0)
	ds_read2_b32 v[60:61], v9 offset0:0 offset1:33
	ds_read2_b32 v[62:63], v9 offset0:66 offset1:99
	ds_read2_b32 v[64:65], v9 offset0:132 offset1:165
	ds_read2_b32 v[66:67], v9 offset0:198 offset1:231
	ds_read2_b32 v[68:69], v9 offset0:8 offset1:41
	ds_read2_b32 v[70:71], v9 offset0:74 offset1:107
	ds_read2_b32 v[72:73], v9 offset0:140 offset1:173
	ds_read2_b32 v[74:75], v9 offset0:206 offset1:239
	ds_read2_b32 v[76:77], v9 offset0:16 offset1:49
	ds_read2_b32 v[78:79], v9 offset0:82 offset1:115
	ds_read2_b32 v[80:81], v9 offset0:148 offset1:181
	ds_read2_b32 v[82:83], v9 offset0:214 offset1:247
	ds_read2_b32 v[84:85], v9 offset0:24 offset1:57
	ds_read2_b32 v[86:87], v9 offset0:90 offset1:123
	ds_read2_b32 v[88:89], v9 offset0:156 offset1:189
	ds_read2_b32 v[90:91], v9 offset0:222 offset1:255
	s_waitcnt lgkmcnt(12)
	v_cvt_pk_bf16_f32 v92, v60, v61
	v_cvt_pk_bf16_f32 v93, v62, v63
	v_cvt_pk_bf16_f32 v94, v64, v65
	v_cvt_pk_bf16_f32 v95, v66, v67
	global_store_dwordx4 v12, v[92:95], s[64:65]
	s_waitcnt lgkmcnt(8)
	v_cvt_pk_bf16_f32 v96, v68, v69
	v_cvt_pk_bf16_f32 v97, v70, v71
	v_cvt_pk_bf16_f32 v98, v72, v73
	v_cvt_pk_bf16_f32 v99, v74, v75
	global_store_dwordx4 v13, v[96:99], s[64:65]
	s_waitcnt lgkmcnt(4)
	v_cvt_pk_bf16_f32 v100, v76, v77
	v_cvt_pk_bf16_f32 v101, v78, v79
	v_cvt_pk_bf16_f32 v102, v80, v81
	v_cvt_pk_bf16_f32 v103, v82, v83
	global_store_dwordx4 v14, v[100:103], s[64:65]
	s_waitcnt lgkmcnt(0)
	v_cvt_pk_bf16_f32 v104, v84, v85
	v_cvt_pk_bf16_f32 v105, v86, v87
	v_cvt_pk_bf16_f32 v106, v88, v89
	v_cvt_pk_bf16_f32 v107, v90, v91
	global_store_dwordx4 v15, v[104:107], s[64:65]
	s_cmpk_lt_i32 s32, 0x100
	s_cbranch_scc0 .Lxpr0p3e_fin
	s_add_i32 s59, s32, 0x800
	s_cmpk_lt_i32 s59, 0x100
	s_cbranch_scc0 .Lxpr0p3e_dumA
	s_lshr_b32 s64, s59, 6
	s_and_b32 s65, s59, 63
	s_mul_i32 s66, s64, 0x80000
	s_lshl_b32 s67, s65, 7
	s_add_i32 s66, s66, s67
	s_add_u32 s66, s60, s66
	s_addc_u32 s67, s61, 0
	v_mov_b32_e32 v11, v5
	global_load_dword v20, v11, s[66:67] nt
	v_add_u32_e32 v11, 0x4000, v11
	global_load_dword v21, v11, s[66:67] nt
	v_add_u32_e32 v11, 0x4000, v11
	global_load_dword v22, v11, s[66:67] nt
	v_add_u32_e32 v11, 0x4000, v11
	global_load_dword v23, v11, s[66:67] nt
	v_add_u32_e32 v11, 0x4000, v11
	global_load_dword v24, v11, s[66:67] nt
	v_add_u32_e32 v11, 0x4000, v11
	global_load_dword v25, v11, s[66:67] nt
	v_add_u32_e32 v11, 0x4000, v11
	global_load_dword v26, v11, s[66:67] nt
	v_add_u32_e32 v11, 0x4000, v11
	global_load_dword v27, v11, s[66:67] nt
	v_add_u32_e32 v11, 0x4000, v11
	global_load_dword v28, v11, s[66:67] nt
	v_add_u32_e32 v11, 0x4000, v11
	global_load_dword v29, v11, s[66:67] nt
	v_add_u32_e32 v11, 0x4000, v11
	global_load_dword v30, v11, s[66:67] nt
	v_add_u32_e32 v11, 0x4000, v11
	global_load_dword v31, v11, s[66:67] nt
	v_add_u32_e32 v11, 0x4000, v11
	global_load_dword v32, v11, s[66:67] nt
	v_add_u32_e32 v11, 0x4000, v11
	global_load_dword v33, v11, s[66:67] nt
	v_add_u32_e32 v11, 0x4000, v11
	global_load_dword v34, v11, s[66:67] nt
	v_add_u32_e32 v11, 0x4000, v11
	global_load_dword v35, v11, s[66:67] nt
	v_add_u32_e32 v11, 0x4000, v11
	global_load_dword v36, v11, s[66:67] nt
	v_add_u32_e32 v11, 0x4000, v11
	global_load_dword v37, v11, s[66:67] nt
	v_add_u32_e32 v11, 0x4000, v11
	global_load_dword v38, v11, s[66:67] nt
	v_add_u32_e32 v11, 0x4000, v11
	global_load_dword v39, v11, s[66:67] nt
	v_add_u32_e32 v11, 0x4000, v11
	global_load_dword v40, v11, s[66:67] nt
	v_add_u32_e32 v11, 0x4000, v11
	global_load_dword v41, v11, s[66:67] nt
	v_add_u32_e32 v11, 0x4000, v11
	global_load_dword v42, v11, s[66:67] nt
	v_add_u32_e32 v11, 0x4000, v11
	global_load_dword v43, v11, s[66:67] nt
	v_add_u32_e32 v11, 0x4000, v11
	global_load_dword v44, v11, s[66:67] nt
	v_add_u32_e32 v11, 0x4000, v11
	global_load_dword v45, v11, s[66:67] nt
	v_add_u32_e32 v11, 0x4000, v11
	global_load_dword v46, v11, s[66:67] nt
	v_add_u32_e32 v11, 0x4000, v11
	global_load_dword v47, v11, s[66:67] nt
	v_add_u32_e32 v11, 0x4000, v11
	global_load_dword v48, v11, s[66:67] nt
	v_add_u32_e32 v11, 0x4000, v11
	global_load_dword v49, v11, s[66:67] nt
	v_add_u32_e32 v11, 0x4000, v11
	global_load_dword v50, v11, s[66:67] nt
	v_add_u32_e32 v11, 0x4000, v11
	global_load_dword v51, v11, s[66:67] nt
	s_branch .Lxpr0p3e_procB

;     __device__ bool next(int i, Unit& u) const {
;         const long L = (long)i * G + c; if (L >= nwg) return false;
;         int wgid = (int)L; { const int q = nwg / NXCD, r = nwg % NXCD, xcd = wgid % NXCD, off = wgid / NXCD; wgid = (xcd < r ? xcd * (q + 1) : r * (q + 1) + (xcd - r) * q) + off; }
;         const int nig = WGM * nN, gid = wgid / nig, fm = gid * WGM, gsz = (nM - fm) < WGM ? (nM - fm) : WGM;
;         u.pm = __builtin_amdgcn_readfirstlane(fm + ((wgid % nig) % gsz)); u.pn = __builtin_amdgcn_readfirstlane((wgid % nig) / gsz); return true;
.Lxpr0p3e_end:
	s_sub_i32 s59, s59, 0x100
	s_movk_i32 s33, 0x84
	s_waitcnt lgkmcnt(0)
	s_barrier
.Lsgp3e_done:
	v_readfirstlane_b32 s8, v212
	s_movk_i32 s6, 0x100
	s_cmpk_gt_i32 s94, 0x1ff
	s_cbranch_scc1 .LBB0_508
	s_ashr_i32 s42, s94, 31
	s_lshr_b32 s0, s42, 29
	s_add_i32 s3, s94, s0
	s_and_b32 s0, s3, -8
	s_sub_i32 s7, s94, s0
	s_cmp_gt_i32 s7, -1
	s_mov_b64 s[0:1], -1
	s_cbranch_scc0 .LBB0_484
	s_lshl_b32 s2, s7, 6
	s_mov_b64 s[0:1], 0

; #define LAS __attribute__((address_space(3)))
; __device__ __forceinline__ void xpose_item(const float* src, int ld, bf16_t* dst, int K, int k0, LAS float* scr, int lane, const float* gk) {
;     if (src) {
; #pragma unroll 8
;         for (int i = 0; i < 32; ++i) { const int kk = 2 * i + (lane >> 5); scr[kk * 33 + (lane & 31)] = __builtin_nontemporal_load(src + (size_t)(k0 + kk) * ld + (lane & 31)); }
;     } else {
; #pragma unroll 8
;         for (int i = 0; i < 32; ++i) { const int kk = 2 * i + (lane >> 5); scr[kk * 33 + (lane & 31)] = 0.f; }
;     }
;     const int c = lane & 7;
;     f32x4 g0 = (f32x4){1.f, 1.f, 1.f, 1.f}, g1 = g0;
;     if (gk) { g0 = *(const f32x4*)(gk + k0 + 8 * c); g1 = *(const f32x4*)(gk + k0 + 8 * c + 4); }
;     asm volatile("s_waitcnt lgkmcnt(0)" ::: "memory");
; #pragma unroll
;     for (int j = 0; j < 4; ++j) { const int n = (lane >> 3) + 8 * j; const LAS float* s = scr + (8 * c) * 33 + n;
; __global__ void __launch_bounds__(512) mega(Args a_byval) {
;     ...
;             it = xpose_all(a.in[23] + (size_t)lyr * D * DFF, a.in[24] + (size_t)lyr * D * DFF, DFF, 2048, 2 * DFF, 2 * DFF, 1, (bf16_t*)(ws + (lyr ? WS_W_GU : WS_W_GU0)), it, NGW, scr, lane, norm_ffn_g + lyr * D);
;             it = xpose_all(a.in[25] + (size_t)lyr * D * DFF, nullptr, 2048, DFF, 2048, 2048, 0, (bf16_t*)(ws + (lyr ? WS_W_D : WS_W_D0)), it, NGW, scr, lane);
.LBB0_507:
	s_waitcnt vmcnt(0)
	s_barrier
	s_cmp_lg_u32 s76, 3
	s_cbranch_scc1 .Lsgp3x_done
	v_readlane_b32 s59, v255, 5
	s_cmpk_lg_i32 s59, 0x100
	s_cbranch_scc1 .Lsgp3x_done
	s_cmpk_lt_i32 s94, 0x80
	s_cbranch_scc1 .Lsgp3x_done
	s_lshl_b32 s59, s94, 3
	s_add_i32 s59, s59, s95
	s_mul_i32 s64, s95, 0x2100
	v_and_b32_e32 v2, 31, v200
	v_lshrrev_b32_e32 v3, 5, v200
	v_lshlrev_b32_e32 v4, 2, v2
	v_mul_u32_u24_e32 v6, 0x84, v3
	v_add3_u32 v6, v6, v4, s64
	v_and_b32_e32 v7, 7, v200
	v_lshrrev_b32_e32 v8, 3, v200
	v_mul_u32_u24_e32 v9, 0x420, v7
	v_lshl_add_u32 v9, v8, 2, v9
	v_add_u32_e32 v9, s64, v9
	s_cmpk_ge_i32 s59, 0x1600
	s_cbranch_scc1 .Lxpf0p3x_end
	s_load_dwordx2 s[60:61], s[92:93], 0xc8
	s_load_dwordx2 s[62:63], s[92:93], 0xe8
	v_mov_b32_e32 v5, 0x2000
	v_mul_u32_u24_e32 v5, v3, v5
	v_add_u32_e32 v5, v5, v4
	v_mov_b32_e32 v10, 0x2c00
	v_mul_u32_u24_e32 v10, v8, v10
	v_lshl_add_u32 v12, v7, 4, v10
	v_add_u32_e32 v13, 0x16000, v12
	v_add_u32_e32 v14, 0x2c000, v12
	v_add_u32_e32 v15, 0x42000, v12
	s_waitcnt lgkmcnt(0)
	s_add_u32 s62, s62, 0x1f800000
	s_addc_u32 s63, s63, 0
	s_lshr_b32 s64, s59, 6
	s_and_b32 s65, s59, 63
	s_mul_i32 s66, s64, 0x80000
	s_lshl_b32 s67, s65, 7
	s_add_i32 s66, s66, s67
	s_add_u32 s66, s60, s66
	s_addc_u32 s67, s61, 0
	v_mov_b32_e32 v11, v5
	global_load_dword v20, v11, s[66:67] nt
	v_add_u32_e32 v11, 0x4000, v11
	global_load_dword v21, v11, s[66:67] nt
	v_add_u32_e32 v11, 0x4000, v11
	global_load_dword v22, v11, s[66:67] nt
	v_add_u32_e32 v11, 0x4000, v11
	global_load_dword v23, v11, s[66:67] nt
	v_add_u32_e32 v11, 0x4000, v11
	global_load_dword v24, v11, s[66:67] nt
	v_add_u32_e32 v11, 0x4000, v11
	global_load_dword v25, v11, s[66:67] nt
	v_add_u32_e32 v11, 0x4000, v11
	global_load_dword v26, v11, s[66:67] nt
	v_add_u32_e32 v11, 0x4000, v11
	global_load_dword v27, v11, s[66:67] nt
	v_add_u32_e32 v11, 0x4000, v11
	global_load_dword v28, v11, s[66:67] nt
	v_add_u32_e32 v11, 0x4000, v11
	global_load_dword v29, v11, s[66:67] nt
	v_add_u32_e32 v11, 0x4000, v11
	global_load_dword v30, v11, s[66:67] nt
	v_add_u32_e32 v11, 0x4000, v11
	global_load_dword v31, v11, s[66:67] nt
	v_add_u32_e32 v11, 0x4000, v11
	global_load_dword v32, v11, s[66:67] nt
	v_add_u32_e32 v11, 0x4000, v11
	global_load_dword v33, v11, s[66:67] nt
	v_add_u32_e32 v11, 0x4000, v11
	global_load_dword v34, v11, s[66:67] nt
	v_add_u32_e32 v11, 0x4000, v11
	global_load_dword v35, v11, s[66:67] nt
	v_add_u32_e32 v11, 0x4000, v11
	global_load_dword v36, v11, s[66:67] nt
	v_add_u32_e32 v11, 0x4000, v11
	global_load_dword v37, v11, s[66:67] nt
	v_add_u32_e32 v11, 0x4000, v11
	global_load_dword v38, v11, s[66:67] nt
	v_add_u32_e32 v11, 0x4000, v11
	global_load_dword v39, v11, s[66:67] nt
	v_add_u32_e32 v11, 0x4000, v11
	global_load_dword v40, v11, s[66:67] nt
	v_add_u32_e32 v11, 0x4000, v11
	global_load_dword v41, v11, s[66:67] nt
	v_add_u32_e32 v11, 0x4000, v11
	global_load_dword v42, v11, s[66:67] nt
	v_add_u32_e32 v11, 0x4000, v11
	global_load_dword v43, v11, s[66:67] nt
	v_add_u32_e32 v11, 0x4000, v11
	global_load_dword v44, v11, s[66:67] nt
	v_add_u32_e32 v11, 0x4000, v11
	global_load_dword v45, v11, s[66:67] nt
	v_add_u32_e32 v11, 0x4000, v11
	global_load_dword v46, v11, s[66:67] nt
	v_add_u32_e32 v11, 0x4000, v11
	global_load_dword v47, v11, s[66:67] nt
	v_add_u32_e32 v11, 0x4000, v11
	global_load_dword v48, v11, s[66:67] nt
	v_add_u32_e32 v11, 0x4000, v11
	global_load_dword v49, v11, s[66:67] nt
	v_add_u32_e32 v11, 0x4000, v11
	global_load_dword v50, v11, s[66:67] nt
	v_add_u32_e32 v11, 0x4000, v11
	global_load_dword v51, v11, s[66:67] nt

; #define LAS __attribute__((address_space(3)))
; __device__ __forceinline__ unsigned xb_xcc_id() { return (unsigned)__builtin_amdgcn_s_getreg((3 << 11) | 20) & 0xFu; }
; __global__ void __launch_bounds__(512) mega(Args a_byval) {
;     ...
;         if (rep + 1 < reps) continue;
;         if (ph + 1 < ph_hi) { if (ph_hi > 64) grid.sync();   else { XcdBarrier xbar; xbar.bar = (unsigned*)(ws + WS_BAR); xbar.x = xb_xcc_id(); xbar.st = (volatile LAS unsigned*)((LAS unsigned char*)lds_raw + 135168); xcd_barrier(xbar); } }
.Lxpr0p3x_end:
	s_sub_i32 s59, s59, 0x100
	s_movk_i32 s33, 0x84
.Lsgp3x_done:
	s_load_dwordx2 s[38:39], s[92:93], 0xe8
	s_mov_b32 s23, 0x10c03000

; __device__ __forceinline__ int xpose_all(const float* src, const float* src2, int ld, int K, int ndst, int nsrc, int mode, bf16_t* dst, int it, int NGW, LAS float* scr, int lane, const float* gvec = nullptr) {
;     ...
;         xpose_item(sp, ld, dst + (size_t)n0 * K, K, kb * 64, scr, lane, gvec);
;     }
;     return it - nitems;
; __global__ void __launch_bounds__(512) mega(Args a_byval) {
;     ...
;             it = xpose_all(a.in[25] + (size_t)lyr * D * DFF, nullptr, 2048, DFF, 2048, 2048, 0, (bf16_t*)(ws + (lyr ? WS_W_D : WS_W_D0)), it, NGW, scr, lane);
;             it = xpose_all(a.in[27] + (size_t)lyr * D * D, nullptr, 2048, 2048, 2048, 2048, 0, (bf16_t*)(ws + (lyr ? WS_W_PG1 : WS_W_PG)), it, NGW, scr, lane, norm_ple_g + lyr * D);
.LBB0_669:
	s_addk_i32 s11, 0xea00
	v_readlane_b32 vcc_lo, v255, 5
	s_cmpk_lg_i32 vcc_lo, 0x100
	s_cbranch_scc1 .Lxs669
	s_addk_i32 s11, 0x800
	s_branch .LBB0_683

; __device__ __forceinline__ int xpose_all(const float* src, const float* src2, int ld, int K, int ndst, int nsrc, int mode, bf16_t* dst, int it, int NGW, LAS float* scr, int lane, const float* gvec = nullptr) {
;     ...
;         xpose_item(sp, ld, dst + (size_t)n0 * K, K, kb * 64, scr, lane, gvec);
;     }
;     return it - nitems;
; __global__ void __launch_bounds__(512) mega(Args a_byval) {
;     ...
;             it = xpose_all(a.in[27] + (size_t)lyr * D * D, nullptr, 2048, 2048, 2048, 2048, 0, (bf16_t*)(ws + (lyr ? WS_W_PG1 : WS_W_PG)), it, NGW, scr, lane, norm_ple_g + lyr * D);
;             it = xpose_all(a.in[26] + (size_t)lyr * PLE * D, nullptr, 2048, 256, 2048, 2048, 0, (bf16_t*)(ws + (lyr ? WS_W_PP1 : WS_W_PP)), it, NGW, scr, lane);
.LBB0_683:
	s_add_i32 s12, s11, 0xfffff800
	v_readlane_b32 vcc_lo, v255, 5
	s_cmpk_lg_i32 vcc_lo, 0x100
	s_cbranch_scc1 .Lxs683
	s_addk_i32 s12, 0x100
	s_branch .LBB0_693
